# consumer v operand: one ds_read_b64 per group (helper writes v transposed per row) instead of four ds_read_u16
# speedup vs baseline: 1.0462x; 1.0093x over previous
; #define LAS3 __attribute__((address_space(3)))
; DEV void rwkv_helper(const Params& p, const Ctx& cx, int l, int unit, int lane, char* ring) {
;   const int d = unit & 1, h = (unit >> 1) & 15, b = unit >> 5;
;   const int j = lane >> 4, s = lane & 15;
;   const h16* SC = (const h16*)(p.ws + OFF_SCAN);
;   const char* pR = (const char*)(SC + 0 * ARR + h * 64);
;   const char* pK = (const char*)(SC + 1 * ARR + h * 64);
;   const char* pV = (const char*)(SC + 2 * ARR + h * 64);
;   const char* pKK = (const char*)(SC + 3 * ARR + h * 64);
;   const char* pA = (const char*)(SC + (size_t)(4 + d) * ARR + h * 64);
;   const char* pW = (const char*)(SC + (size_t)(6 + d) * ARR + h * 64);
;   const int jm = d ? 3 - j : j;
;   const unsigned vo0 = (unsigned)(jm * 2048 + s * 8);
;   f4v ka4, om4;
;   {
;     float4 t = *(const float4*)(p.rwkv_k_a + (size_t)l * 1024 + h * 64 + 4 * s);
;     ka4 = f4v{t.x, t.y, t.z, t.w};
;     om4 = 1.f - ka4;
;   }
;   struct RGH { u2v w, a, kk, k, r, v; };
;   RGH q0, q1, q2, q3, q4, q5, q6, q7;
;   const unsigned wofs = (unsigned)(j * 128 + s * 8);
;   const unsigned vwofs = (unsigned)(2560 + j * 128 + s * 8);
;   LAS3 volatile int* pflag = (LAS3 volatile int*)(ring + RW_FLAGS);
;   LAS3 volatile int* cflag = (LAS3 volatile int*)(ring + RW_FLAGS + 64);
;   int cmin = 0;
;     ...
;   RH_LOAD(q0, 0); RH_LOAD(q1, 1); RH_LOAD(q2, 2); RH_LOAD(q3, 3); RH_LOAD(q4, 4); RH_LOAD(q5, 5); RH_LOAD(q6, 6); RH_LOAD(q7, 7);
.LBB0_177:
	s_waitcnt lgkmcnt(0)
	s_barrier
	s_and_saveexec_b64 s[42:43], s[70:71]
	ds_write_b32 v118, v129 offset:49152
	s_or_b64 exec, exec, s[42:43]
	s_and_b32 s34, s31, 63
	s_and_b64 vcc, exec, s[72:73]
	s_waitcnt lgkmcnt(0)
	s_barrier
	s_cbranch_vccz .LBB0_223
	s_mov_b64 s[88:89], 0
	s_and_b64 vcc, exec, s[68:69]
	s_mov_b64 s[42:43], 0
	s_cbranch_vccz .LBB0_224
	s_setprio 1
	v_lshl_add_u32 v183, v116, 1, v116
	v_mul_u32_u24_e32 v182, 0x7e, v107
	v_sub_u32_e32 v182, v183, v182
	s_lshl_b32 s0, s34, 5
	s_and_b32 s5, s0, 0x3c0
	s_and_b32 s23, s31, 1
	s_bfe_i32 s4, s31, 0x10000
	s_lshr_b32 s22, s34, 5
	s_lshl_b32 s10, s5, 1
	s_add_u32 s94, s2, s10
	s_addc_u32 s95, s3, 0
	v_readlane_b32 s0, v241, 30
	v_readlane_b32 s1, v241, 31
	s_add_u32 s97, s0, s10
	s_addc_u32 s99, s1, 0
	v_readlane_b32 s0, v241, 32
	v_readlane_b32 s1, v241, 33
	s_add_u32 s0, s0, s10
	s_addc_u32 s1, s1, 0
	v_readlane_b32 s36, v241, 42
	v_readlane_b32 s37, v241, 43
	s_add_u32 s8, s36, s10
	s_addc_u32 s84, s37, 0
	s_mul_i32 s33, s23, 0x4100000
	s_add_u32 s33, s2, s33
	s_addc_u32 s35, s3, 0
	s_add_u32 s10, s33, s10
	s_addc_u32 s33, s35, 0
	s_add_u32 s85, s10, 0x10400000
	s_addc_u32 s86, s33, 0
	s_add_u32 s87, s10, 0x18600000
	s_addc_u32 s35, s33, 0
	s_lshl_b32 s33, s22, 8
	s_bitset1_b32 s33, 15
	s_and_b32 s4, s4, 0xfc
	s_or_b32 s4, s33, s4
	s_lshl_b32 s10, s5, 2
	s_lshl_b32 s42, s4, 11
	s_add_u32 s4, s87, s42
	s_addc_u32 s5, s35, 0
	s_add_u32 s36, s85, s42
	s_addc_u32 s37, s86, 0
	s_add_u32 s44, s8, s42
	s_addc_u32 s45, s84, 0
	s_add_u32 s90, s97, s42
	s_addc_u32 s91, s99, 0
	s_add_u32 s92, s94, s42
	s_addc_u32 s93, s95, 0
	s_add_u32 vcc_lo, s0, s42
	s_addc_u32 vcc_hi, s1, 0
	s_cmp_eq_u32 s23, 0
	s_cselect_b64 s[42:43], -1, 0
	v_cndmask_b32_e64 v0, v109, v108, s[42:43]
	v_or_b32_e32 v119, v0, v110
	v_lshl_add_u64 v[0:1], v[80:81], 0, s[10:11]
	s_waitcnt vmcnt(0)
	v_mov_b32_e32 v8, v119
	global_load_dwordx4 v[0:3], v[0:1], off
	global_load_dwordx2 v[4:5], v8, s[4:5]
	global_load_dwordx2 v[36:37], v8, s[36:37]
	global_load_dwordx2 v[6:7], v8, s[44:45]
	global_load_dwordx2 v[44:45], v8, s[90:91]
	global_load_dwordx2 v[38:39], v8, s[92:93]
	global_load_dwordx2 v[42:43], v8, vcc
	s_and_b64 s[4:5], s[42:43], exec
	s_cselect_b32 s4, 4, 0xf8
	s_cselect_b32 s37, 8, 0xf4
	s_cselect_b32 s44, 12, 0xf0
	s_cselect_b32 s45, 16, 0xec
	s_cselect_b32 s36, 20, 0xe8
	s_cselect_b32 s23, 24, 0xe4
	s_cselect_b32 s10, 28, 0xe0
	s_or_b32 s4, s33, s4
	s_lshl_b32 s90, s4, 11
	s_add_u32 s4, s87, s90
	v_mov_b32_e32 v12, v119
	s_addc_u32 s5, s35, 0
	global_load_dwordx2 v[8:9], v12, s[4:5]
	s_add_u32 s4, s85, s90
	s_addc_u32 s5, s86, 0
	global_load_dwordx2 v[40:41], v12, s[4:5]
	s_add_u32 s4, s8, s90
	s_addc_u32 s5, s84, 0
	global_load_dwordx2 v[10:11], v12, s[4:5]
	s_add_u32 s4, s97, s90
	s_addc_u32 s5, s99, 0
	global_load_dwordx2 v[52:53], v12, s[4:5]
	s_add_u32 s4, s94, s90
	s_addc_u32 s5, s95, 0
	global_load_dwordx2 v[46:47], v12, s[4:5]
	s_add_u32 s4, s0, s90
	s_addc_u32 s5, s1, 0
	global_load_dwordx2 v[50:51], v12, s[4:5]
	s_or_b32 s4, s33, s37
	s_lshl_b32 s37, s4, 11
	s_add_u32 s4, s87, s37
	v_mov_b32_e32 v16, v119
	s_addc_u32 s5, s35, 0
	global_load_dwordx2 v[12:13], v16, s[4:5]
	s_add_u32 s4, s85, s37
	s_addc_u32 s5, s86, 0
	global_load_dwordx2 v[48:49], v16, s[4:5]
	s_add_u32 s4, s8, s37
	s_addc_u32 s5, s84, 0
	global_load_dwordx2 v[14:15], v16, s[4:5]
	s_add_u32 s4, s97, s37
	s_addc_u32 s5, s99, 0
	global_load_dwordx2 v[60:61], v16, s[4:5]
	s_add_u32 s4, s94, s37
	s_addc_u32 s5, s95, 0
	global_load_dwordx2 v[54:55], v16, s[4:5]
	s_add_u32 s4, s0, s37
	s_addc_u32 s5, s1, 0
	global_load_dwordx2 v[58:59], v16, s[4:5]
	s_or_b32 s4, s33, s44
	s_lshl_b32 s37, s4, 11
	s_add_u32 s4, s87, s37
	v_mov_b32_e32 v20, v119
	s_addc_u32 s5, s35, 0
	global_load_dwordx2 v[16:17], v20, s[4:5]
	s_add_u32 s4, s85, s37
	s_addc_u32 s5, s86, 0
	global_load_dwordx2 v[56:57], v20, s[4:5]
	s_add_u32 s4, s8, s37
	s_addc_u32 s5, s84, 0
	global_load_dwordx2 v[18:19], v20, s[4:5]
	s_add_u32 s4, s97, s37
	s_addc_u32 s5, s99, 0
	global_load_dwordx2 v[66:67], v20, s[4:5]
	s_add_u32 s4, s94, s37
	s_addc_u32 s5, s95, 0
	global_load_dwordx2 v[62:63], v20, s[4:5]
	s_add_u32 s4, s0, s37
	s_addc_u32 s5, s1, 0
	global_load_dwordx2 v[68:69], v20, s[4:5]
	s_or_b32 s4, s33, s45
	s_lshl_b32 s37, s4, 11
	s_add_u32 s4, s87, s37
	v_mov_b32_e32 v24, v119
	s_addc_u32 s5, s35, 0
	global_load_dwordx2 v[20:21], v24, s[4:5]
	s_add_u32 s4, s85, s37
	s_addc_u32 s5, s86, 0
	global_load_dwordx2 v[64:65], v24, s[4:5]
	s_add_u32 s4, s8, s37
	s_addc_u32 s5, s84, 0
	global_load_dwordx2 v[22:23], v24, s[4:5]
	s_add_u32 s4, s97, s37
	s_addc_u32 s5, s99, 0
	global_load_dwordx2 v[76:77], v24, s[4:5]
	s_add_u32 s4, s94, s37
	s_addc_u32 s5, s95, 0
	global_load_dwordx2 v[70:71], v24, s[4:5]
	s_add_u32 s4, s0, s37
	s_addc_u32 s5, s1, 0
	global_load_dwordx2 v[74:75], v24, s[4:5]
	s_or_b32 s4, s33, s36
	s_lshl_b32 s36, s4, 11
	s_add_u32 s4, s87, s36
	v_mov_b32_e32 v28, v119
	s_addc_u32 s5, s35, 0
	global_load_dwordx2 v[24:25], v28, s[4:5]
	s_add_u32 s4, s85, s36
	s_addc_u32 s5, s86, 0
	global_load_dwordx2 v[72:73], v28, s[4:5]
	s_add_u32 s4, s8, s36
	s_addc_u32 s5, s84, 0
	global_load_dwordx2 v[26:27], v28, s[4:5]
	s_add_u32 s4, s97, s36
	s_addc_u32 s5, s99, 0
	global_load_dwordx2 v[84:85], v28, s[4:5]
	s_add_u32 s4, s94, s36
	s_addc_u32 s5, s95, 0
	global_load_dwordx2 v[78:79], v28, s[4:5]
	s_add_u32 s4, s0, s36
	s_addc_u32 s5, s1, 0
	global_load_dwordx2 v[86:87], v28, s[4:5]
	s_or_b32 s4, s33, s23
	s_lshl_b32 s23, s4, 11
	s_add_u32 s4, s87, s23
	v_mov_b32_e32 v32, v119
	s_addc_u32 s5, s35, 0
	global_load_dwordx2 v[28:29], v32, s[4:5]
	s_add_u32 s4, s85, s23
	s_addc_u32 s5, s86, 0
	global_load_dwordx2 v[82:83], v32, s[4:5]
	s_add_u32 s4, s8, s23
	s_addc_u32 s5, s84, 0
	global_load_dwordx2 v[30:31], v32, s[4:5]
	s_add_u32 s4, s97, s23
	s_addc_u32 s5, s99, 0
	global_load_dwordx2 v[98:99], v32, s[4:5]
	s_add_u32 s4, s94, s23
	s_addc_u32 s5, s95, 0
	global_load_dwordx2 v[88:89], v32, s[4:5]
	s_add_u32 s4, s0, s23
	s_addc_u32 s5, s1, 0
	global_load_dwordx2 v[96:97], v32, s[4:5]
	s_or_b32 s4, s33, s10
	s_lshl_b32 s10, s4, 11
	s_add_u32 s4, s87, s10
	v_mov_b32_e32 v92, v119
	s_addc_u32 s5, s35, 0
	global_load_dwordx2 v[32:33], v92, s[4:5]
	s_add_u32 s4, s85, s10
	s_addc_u32 s5, s86, 0
	global_load_dwordx2 v[90:91], v92, s[4:5]
	s_add_u32 s4, s8, s10
	s_addc_u32 s5, s84, 0
	global_load_dwordx2 v[34:35], v92, s[4:5]
	s_add_u32 s4, s97, s10
	s_addc_u32 s5, s99, 0
	global_load_dwordx2 v[102:103], v92, s[4:5]
	s_add_u32 s4, s94, s10
	s_addc_u32 s5, s95, 0
	global_load_dwordx2 v[100:101], v92, s[4:5]
	s_add_u32 s4, s0, s10
	s_addc_u32 s5, s1, 0
	global_load_dwordx2 v[104:105], v92, s[4:5]
	s_mov_b32 s36, 0
	s_waitcnt vmcnt(48)
	v_sub_f32_e32 v93, 1.0, v3
	v_sub_f32_e32 v92, 1.0, v2
	v_sub_f32_e32 v95, 1.0, v1
	v_sub_f32_e32 v94, 1.0, v0
	s_lshl_b32 s10, s22, 14
	s_mov_b32 s37, 0
	s_branch .LBB0_183
.LBB0_182:
	s_min_u32 s4, s37, 0x1030
	s_lshl_b32 s4, s4, 2
	s_cmp_gt_u32 s37, 48
	s_cselect_b32 s5, 0xffffff3c, 60
	s_cselect_b32 s23, s10, s33
	s_cselect_b32 s37, s46, 0xfc
	s_add_i32 s44, s4, s5
	s_sub_i32 s37, s37, s44
	s_waitcnt vmcnt(46)
	v_cvt_f32_f16_sdwa v123, v90 dst_sel:DWORD dst_unused:UNUSED_PAD src0_sel:WORD_1
	v_cvt_f32_f16_sdwa v125, v91 dst_sel:DWORD dst_unused:UNUSED_PAD src0_sel:WORD_1
	v_cvt_f32_f16_e32 v122, v90
	v_cvt_f32_f16_e32 v124, v91
	s_and_b64 s[4:5], s[42:43], exec
	s_waitcnt vmcnt(44)
	v_cvt_f32_f16_sdwa v127, v102 dst_sel:DWORD dst_unused:UNUSED_PAD src0_sel:WORD_1
	v_cvt_f32_f16_sdwa v133, v103 dst_sel:DWORD dst_unused:UNUSED_PAD src0_sel:WORD_1
	v_cvt_f32_f16_e32 v126, v102
	v_cvt_f32_f16_e32 v132, v103
	s_cselect_b32 s4, s44, s37
	s_add_i32 s4, s4, s23
	s_ashr_i32 s5, s4, 31
	v_pk_fma_f32 v[102:103], v[2:3], v[124:125], v[92:93]
	v_pk_fma_f32 v[122:123], v[0:1], v[122:123], v[94:95]
	s_lshl_b64 s[4:5], s[4:5], 11
	v_pk_mul_f32 v[102:103], v[102:103], v[132:133]
	v_pk_mul_f32 v[126:127], v[122:123], v[126:127]
	s_add_u32 s44, s87, s4
	v_pk_mul_f16 v123, v91, v35
	v_pk_mul_f16 v122, v90, v34
	v_cvt_pk_f16_f32 v125, v102, v103
	v_cvt_pk_f16_f32 v124, v126, v127
	ds_write_b128 v120, v[32:35] offset:21504
	ds_write_b128 v120, v[122:125] offset:22528
	s_waitcnt vmcnt(42)
	ds_write_b64 v121, v[100:101] offset:23552
	v_add_u32_e32 v181, v121, v182
	ds_write_b16 v181, v104 offset:24064
	ds_write_b16_d16_hi v181, v104 offset:24072
	ds_write_b16 v181, v105 offset:24080
	ds_write_b16_d16_hi v181, v105 offset:24088
	v_mov_b32_e32 v32, s22
	v_mov_b32_e32 v104, v119
	s_addc_u32 s45, s35, s5
	s_waitcnt lgkmcnt(0)
	ds_write_b32 v161, v32 offset:49152
	global_load_dwordx2 v[32:33], v104, s[44:45]
	s_add_u32 s44, s85, s4
	s_addc_u32 s45, s86, s5
	global_load_dwordx2 v[90:91], v104, s[44:45]
	s_add_u32 s44, s8, s4
	s_addc_u32 s45, s84, s5
	global_load_dwordx2 v[34:35], v104, s[44:45]
	s_add_u32 s44, s97, s4
	s_addc_u32 s45, s99, s5
	global_load_dwordx2 v[102:103], v104, s[44:45]
	s_add_u32 s44, s94, s4
	s_addc_u32 s45, s95, s5
	s_add_u32 s4, s0, s4
	s_addc_u32 s5, s1, s5
	global_load_dwordx2 v[100:101], v104, s[44:45]
	s_nop 0
	global_load_dwordx2 v[104:105], v104, s[4:5]
	s_andn2_b64 vcc, exec, s[90:91]
	s_mov_b32 s37, s22
	s_cbranch_vccz .LBB0_242

; DEV void rwkv_helper(const Params& p, const Ctx& cx, int l, int unit, int lane, char* ring) {
;     ...
;   RH_LOAD(q0, 0); RH_LOAD(q1, 1); RH_LOAD(q2, 2); RH_LOAD(q3, 3); RH_LOAD(q4, 4); RH_LOAD(q5, 5); RH_LOAD(q6, 6); RH_LOAD(q7, 7);
; #pragma unroll 1
;   for (int g = 0; g < RW_NG; g += 8) {
;     RH_STEP(q0, g); RH_LOAD(q0, g + 8); __builtin_amdgcn_sched_barrier(0);
;     RH_STEP(q1, g + 1); RH_LOAD(q1, g + 9); __builtin_amdgcn_sched_barrier(0);
;     RH_STEP(q2, g + 2); RH_LOAD(q2, g + 10); __builtin_amdgcn_sched_barrier(0);
;     RH_STEP(q3, g + 3); RH_LOAD(q3, g + 11); __builtin_amdgcn_sched_barrier(0);
;     RH_STEP(q4, g + 4); RH_LOAD(q4, g + 12); __builtin_amdgcn_sched_barrier(0);
;     RH_STEP(q5, g + 5); RH_LOAD(q5, g + 13); __builtin_amdgcn_sched_barrier(0);
;     RH_STEP(q6, g + 6); RH_LOAD(q6, g + 14); __builtin_amdgcn_sched_barrier(0);
;     RH_STEP(q7, g + 7); RH_LOAD(q7, g + 15); __builtin_amdgcn_sched_barrier(0);
.LBB0_185:
	s_waitcnt vmcnt(46)
	v_cvt_f32_f16_sdwa v121, v36 dst_sel:DWORD dst_unused:UNUSED_PAD src0_sel:WORD_1
	v_cvt_f32_f16_e32 v120, v36
	s_waitcnt vmcnt(44)
	v_cvt_f32_f16_sdwa v125, v44 dst_sel:DWORD dst_unused:UNUSED_PAD src0_sel:WORD_1
	v_cvt_f32_f16_e32 v124, v44
	s_and_b32 s4, s37, 8
	v_cvt_f32_f16_sdwa v123, v37 dst_sel:DWORD dst_unused:UNUSED_PAD src0_sel:WORD_1
	v_cvt_f32_f16_e32 v122, v37
	s_mulk_i32 s4, 0xc00
	s_add_i32 s4, s4, 16
	v_pk_fma_f32 v[120:121], v[0:1], v[120:121], v[94:95]
	s_or_b32 s23, s37, 1
	s_add_i32 s22, s37, 8
	v_pk_mul_f32 v[120:121], v[120:121], v[124:125]
	s_cmpk_gt_u32 s37, 0x1037
	v_cvt_f32_f16_sdwa v127, v45 dst_sel:DWORD dst_unused:UNUSED_PAD src0_sel:WORD_1
	v_cvt_f32_f16_e32 v126, v45
	v_pk_fma_f32 v[44:45], v[2:3], v[122:123], v[92:93]
	v_pk_mul_f16 v122, v36, v6
	v_cvt_pk_f16_f32 v124, v120, v121
	v_add_u32_e32 v36, s4, v113
	v_add_u32_e32 v121, s4, v111
	s_cselect_b64 s[90:91], -1, 0
	s_lshl_b32 s4, s22, 2
	s_cmpk_lt_u32 s37, 0x1038
	s_cselect_b32 s4, s4, 0x40fc
	s_add_i32 s5, s4, 0xffffff00
	s_min_u32 s44, s5, s4
	s_cmpk_gt_u32 s4, 0xff
	s_movk_i32 s4, 0x3fff
	s_cselect_b32 s4, s4, 0xff
	s_cselect_b32 s45, s10, s33
	s_sub_i32 s4, s4, s44
	s_add_i32 vcc_lo, s4, -3
	s_and_b64 s[4:5], s[42:43], exec
	s_cselect_b32 s4, s44, vcc_lo
	s_add_i32 s4, s4, s45
	s_ashr_i32 s5, s4, 31
	s_lshl_b64 s[4:5], s[4:5], 11
	v_pk_mul_f32 v[44:45], v[44:45], v[126:127]
	v_add_u32_e32 v120, v36, v128
	s_add_u32 s44, s87, s4
	v_pk_mul_f16 v123, v37, v7
	v_cvt_pk_f16_f32 v125, v44, v45
	ds_write_b128 v120, v[4:7]
	ds_write_b128 v120, v[122:125] offset:1024
	s_waitcnt vmcnt(42)
	ds_write_b64 v121, v[38:39] offset:2048
	v_add_u32_e32 v181, v121, v182
	ds_write_b16 v181, v42 offset:2560
	ds_write_b16_d16_hi v181, v42 offset:2568
	ds_write_b16 v181, v43 offset:2576
	ds_write_b16_d16_hi v181, v43 offset:2584
	v_mov_b32_e32 v4, s23
	v_mov_b32_e32 v42, v119
	s_addc_u32 s45, s35, s5
	s_waitcnt lgkmcnt(0)
	ds_write_b32 v161, v4 offset:49152
	global_load_dwordx2 v[4:5], v42, s[44:45]
	s_add_u32 s44, s85, s4
	s_addc_u32 s45, s86, s5
	global_load_dwordx2 v[36:37], v42, s[44:45]
	s_add_u32 s44, s8, s4
	s_addc_u32 s45, s84, s5
	global_load_dwordx2 v[6:7], v42, s[44:45]
	s_add_u32 s44, s97, s4
	s_addc_u32 s45, s99, s5
	global_load_dwordx2 v[44:45], v42, s[44:45]
	s_add_u32 s44, s94, s4
	s_addc_u32 s45, s95, s5
	s_add_u32 s4, s0, s4
	s_addc_u32 s5, s1, s5
	global_load_dwordx2 v[38:39], v42, s[44:45]
	s_nop 0
	global_load_dwordx2 v[42:43], v42, s[4:5]
	v_cndmask_b32_e64 v122, 0, 1, s[92:93]
	v_cmp_ne_u32_e64 s[44:45], 1, v122
	s_andn2_b64 vcc, exec, s[92:93]
	s_cbranch_vccnz .LBB0_187
	s_add_i32 s4, s37, -14
	s_cmp_ge_i32 s36, s4
	s_cbranch_scc0 .LBB0_203
.LBB0_187:
	s_waitcnt vmcnt(46)
	v_cvt_f32_f16_sdwa v123, v40 dst_sel:DWORD dst_unused:UNUSED_PAD src0_sel:WORD_1
	v_cvt_f32_f16_sdwa v125, v41 dst_sel:DWORD dst_unused:UNUSED_PAD src0_sel:WORD_1
	v_cvt_f32_f16_e32 v122, v40
	v_cvt_f32_f16_e32 v124, v41
	s_waitcnt vmcnt(44)
	v_cvt_f32_f16_sdwa v127, v52 dst_sel:DWORD dst_unused:UNUSED_PAD src0_sel:WORD_1
	v_cvt_f32_f16_sdwa v133, v53 dst_sel:DWORD dst_unused:UNUSED_PAD src0_sel:WORD_1
	v_cvt_f32_f16_e32 v126, v52
	v_cvt_f32_f16_e32 v132, v53
	s_and_b32 s4, s23, 9
	s_mulk_i32 s4, 0xc00
	s_add_i32 s4, s4, 16
	v_pk_fma_f32 v[52:53], v[2:3], v[124:125], v[92:93]
	v_pk_fma_f32 v[122:123], v[0:1], v[122:123], v[94:95]
	v_pk_mul_f32 v[52:53], v[52:53], v[132:133]
	v_pk_mul_f32 v[126:127], v[122:123], v[126:127]
	v_pk_mul_f16 v122, v40, v10
	v_add3_u32 v40, s4, v113, v128
	v_pk_mul_f16 v123, v41, v11
	v_cvt_pk_f16_f32 v125, v52, v53
	v_cvt_pk_f16_f32 v124, v126, v127
	ds_write_b128 v40, v[8:11]
	ds_write_b128 v40, v[122:125] offset:1024
	v_add_u32_e32 v8, s4, v111
	s_or_b32 s4, s37, 2
	s_waitcnt vmcnt(42)
	ds_write_b64 v8, v[46:47] offset:2048
	v_add_u32_e32 v181, v8, v182
	ds_write_b16 v181, v50 offset:2560
	ds_write_b16_d16_hi v181, v50 offset:2568
	ds_write_b16 v181, v51 offset:2576
	ds_write_b16_d16_hi v181, v51 offset:2584
	v_mov_b32_e32 v8, s4
	s_min_u32 s4, s37, 0x1036
	s_lshl_b32 s4, s4, 2
	s_cmp_gt_u32 s37, 54
	s_cselect_b32 s5, 0xffffff24, 36
	s_cselect_b32 s23, s10, s33
	s_cselect_b32 s92, s46, 0xfc
	s_add_i32 s93, s4, s5
	s_sub_i32 s92, s92, s93
	s_and_b64 s[4:5], s[42:43], exec
	s_cselect_b32 s4, s93, s92
	s_add_i32 s4, s4, s23
	s_ashr_i32 s5, s4, 31
	s_lshl_b64 s[4:5], s[4:5], 11
	s_add_u32 s92, s87, s4
	v_mov_b32_e32 v50, v119
	s_addc_u32 s93, s35, s5
	s_waitcnt lgkmcnt(0)
	ds_write_b32 v161, v8 offset:49152
	global_load_dwordx2 v[8:9], v50, s[92:93]
	s_add_u32 s92, s85, s4
	s_addc_u32 s93, s86, s5
	global_load_dwordx2 v[40:41], v50, s[92:93]
	s_add_u32 s92, s8, s4
	s_addc_u32 s93, s84, s5
	global_load_dwordx2 v[10:11], v50, s[92:93]
	s_add_u32 s92, s97, s4
	s_addc_u32 s93, s99, s5
	global_load_dwordx2 v[52:53], v50, s[92:93]
	s_add_u32 s92, s94, s4
	s_addc_u32 s93, s95, s5
	s_add_u32 s4, s0, s4
	s_addc_u32 s5, s1, s5
	global_load_dwordx2 v[46:47], v50, s[92:93]
	s_nop 0
	global_load_dwordx2 v[50:51], v50, s[4:5]
	s_and_b64 vcc, exec, s[44:45]
	s_cbranch_vccnz .LBB0_189
	s_add_i32 s4, s37, -13
	s_cmp_ge_i32 s36, s4
	s_cbranch_scc0 .LBB0_206
; DEV void rwkv_helper(const Params& p, const Ctx& cx, int l, int unit, int lane, char* ring) {
;     ...
;   RH_LOAD(q0, 0); RH_LOAD(q1, 1); RH_LOAD(q2, 2); RH_LOAD(q3, 3); RH_LOAD(q4, 4); RH_LOAD(q5, 5); RH_LOAD(q6, 6); RH_LOAD(q7, 7);
; #pragma unroll 1
;   for (int g = 0; g < RW_NG; g += 8) {
;     RH_STEP(q0, g); RH_LOAD(q0, g + 8); __builtin_amdgcn_sched_barrier(0);
;     RH_STEP(q1, g + 1); RH_LOAD(q1, g + 9); __builtin_amdgcn_sched_barrier(0);
;     RH_STEP(q2, g + 2); RH_LOAD(q2, g + 10); __builtin_amdgcn_sched_barrier(0);
;     RH_STEP(q3, g + 3); RH_LOAD(q3, g + 11); __builtin_amdgcn_sched_barrier(0);
;     RH_STEP(q4, g + 4); RH_LOAD(q4, g + 12); __builtin_amdgcn_sched_barrier(0);
;     RH_STEP(q5, g + 5); RH_LOAD(q5, g + 13); __builtin_amdgcn_sched_barrier(0);
;     RH_STEP(q6, g + 6); RH_LOAD(q6, g + 14); __builtin_amdgcn_sched_barrier(0);
;     RH_STEP(q7, g + 7); RH_LOAD(q7, g + 15); __builtin_amdgcn_sched_barrier(0);
.LBB0_189:
	s_waitcnt vmcnt(46)
	v_cvt_f32_f16_sdwa v123, v48 dst_sel:DWORD dst_unused:UNUSED_PAD src0_sel:WORD_1
	v_cvt_f32_f16_sdwa v125, v49 dst_sel:DWORD dst_unused:UNUSED_PAD src0_sel:WORD_1
	v_cvt_f32_f16_e32 v122, v48
	v_cvt_f32_f16_e32 v124, v49
	s_waitcnt vmcnt(44)
	v_cvt_f32_f16_sdwa v127, v60 dst_sel:DWORD dst_unused:UNUSED_PAD src0_sel:WORD_1
	v_cvt_f32_f16_sdwa v133, v61 dst_sel:DWORD dst_unused:UNUSED_PAD src0_sel:WORD_1
	v_cvt_f32_f16_e32 v126, v60
	v_cvt_f32_f16_e32 v132, v61
	v_pk_fma_f32 v[60:61], v[2:3], v[124:125], v[92:93]
	v_pk_fma_f32 v[122:123], v[0:1], v[122:123], v[94:95]
	s_or_b32 s4, s37, 3
	v_pk_mul_f32 v[60:61], v[60:61], v[132:133]
	v_pk_mul_f32 v[126:127], v[122:123], v[126:127]
	v_pk_mul_f16 v123, v49, v15
	v_pk_mul_f16 v122, v48, v14
	v_cvt_pk_f16_f32 v125, v60, v61
	v_cvt_pk_f16_f32 v124, v126, v127
	ds_write_b128 v120, v[12:15] offset:6144
	ds_write_b128 v120, v[122:125] offset:7168
	s_waitcnt vmcnt(42)
	ds_write_b64 v121, v[54:55] offset:8192
	v_add_u32_e32 v181, v121, v182
	ds_write_b16 v181, v58 offset:8704
	ds_write_b16_d16_hi v181, v58 offset:8712
	ds_write_b16 v181, v59 offset:8720
	ds_write_b16_d16_hi v181, v59 offset:8728
	v_mov_b32_e32 v12, s4
	s_min_u32 s4, s37, 0x1035
	s_lshl_b32 s4, s4, 2
	s_cmp_gt_u32 s37, 53
	s_cselect_b32 s5, 0xffffff28, 40
	s_cselect_b32 s23, s10, s33
	s_cselect_b32 s92, s46, 0xfc
	s_add_i32 s93, s4, s5
	s_sub_i32 s92, s92, s93
	s_and_b64 s[4:5], s[42:43], exec
	s_cselect_b32 s4, s93, s92
	s_add_i32 s4, s4, s23
	s_ashr_i32 s5, s4, 31
	s_lshl_b64 s[4:5], s[4:5], 11
	s_add_u32 s92, s87, s4
	v_mov_b32_e32 v58, v119
	s_addc_u32 s93, s35, s5
	s_waitcnt lgkmcnt(0)
	ds_write_b32 v161, v12 offset:49152
	global_load_dwordx2 v[12:13], v58, s[92:93]
	s_add_u32 s92, s85, s4
	s_addc_u32 s93, s86, s5
	global_load_dwordx2 v[48:49], v58, s[92:93]
	s_add_u32 s92, s8, s4
	s_addc_u32 s93, s84, s5
	global_load_dwordx2 v[14:15], v58, s[92:93]
	s_add_u32 s92, s97, s4
	s_addc_u32 s93, s99, s5
	global_load_dwordx2 v[60:61], v58, s[92:93]
	s_add_u32 s92, s94, s4
	s_addc_u32 s93, s95, s5
	s_add_u32 s4, s0, s4
	s_addc_u32 s5, s1, s5
	global_load_dwordx2 v[54:55], v58, s[92:93]
	s_nop 0
	global_load_dwordx2 v[58:59], v58, s[4:5]
	s_and_b64 vcc, exec, s[44:45]
	s_cbranch_vccnz .LBB0_191
	s_add_i32 s4, s37, -12
	s_cmp_ge_i32 s36, s4
	s_cbranch_scc0 .LBB0_209
.LBB0_191:
	s_waitcnt vmcnt(46)
	v_cvt_f32_f16_sdwa v123, v56 dst_sel:DWORD dst_unused:UNUSED_PAD src0_sel:WORD_1
	v_cvt_f32_f16_sdwa v125, v57 dst_sel:DWORD dst_unused:UNUSED_PAD src0_sel:WORD_1
	v_cvt_f32_f16_e32 v122, v56
	v_cvt_f32_f16_e32 v124, v57
	s_waitcnt vmcnt(44)
	v_cvt_f32_f16_sdwa v127, v66 dst_sel:DWORD dst_unused:UNUSED_PAD src0_sel:WORD_1
	v_cvt_f32_f16_sdwa v133, v67 dst_sel:DWORD dst_unused:UNUSED_PAD src0_sel:WORD_1
	v_cvt_f32_f16_e32 v126, v66
	v_cvt_f32_f16_e32 v132, v67
	v_pk_fma_f32 v[66:67], v[2:3], v[124:125], v[92:93]
	v_pk_fma_f32 v[122:123], v[0:1], v[122:123], v[94:95]
	s_or_b32 s4, s37, 4
	v_pk_mul_f32 v[66:67], v[66:67], v[132:133]
	v_pk_mul_f32 v[126:127], v[122:123], v[126:127]
	v_pk_mul_f16 v123, v57, v19
	v_pk_mul_f16 v122, v56, v18
	v_cvt_pk_f16_f32 v125, v66, v67
	v_cvt_pk_f16_f32 v124, v126, v127
	ds_write_b128 v120, v[16:19] offset:9216
	ds_write_b128 v120, v[122:125] offset:10240
	s_waitcnt vmcnt(42)
	ds_write_b64 v121, v[62:63] offset:11264
	v_add_u32_e32 v181, v121, v182
	ds_write_b16 v181, v68 offset:11776
	ds_write_b16_d16_hi v181, v68 offset:11784
	ds_write_b16 v181, v69 offset:11792
	ds_write_b16_d16_hi v181, v69 offset:11800
	v_mov_b32_e32 v16, s4
	s_min_u32 s4, s37, 0x1034
	s_lshl_b32 s4, s4, 2
	s_cmp_gt_u32 s37, 52
	s_cselect_b32 s5, 0xffffff2c, 44
	s_cselect_b32 s23, s10, s33
	s_cselect_b32 s92, s46, 0xfc
	s_add_i32 s93, s4, s5
	s_sub_i32 s92, s92, s93
	s_and_b64 s[4:5], s[42:43], exec
	s_cselect_b32 s4, s93, s92
	s_add_i32 s4, s4, s23
	s_ashr_i32 s5, s4, 31
	s_lshl_b64 s[4:5], s[4:5], 11
	s_add_u32 s92, s87, s4
	v_mov_b32_e32 v68, v119
	s_addc_u32 s93, s35, s5
	s_waitcnt lgkmcnt(0)
	ds_write_b32 v161, v16 offset:49152
	global_load_dwordx2 v[16:17], v68, s[92:93]
	s_add_u32 s92, s85, s4
	s_addc_u32 s93, s86, s5
	global_load_dwordx2 v[56:57], v68, s[92:93]
	s_add_u32 s92, s8, s4
	s_addc_u32 s93, s84, s5
	global_load_dwordx2 v[18:19], v68, s[92:93]
	s_add_u32 s92, s97, s4
	s_addc_u32 s93, s99, s5
	global_load_dwordx2 v[66:67], v68, s[92:93]
	s_add_u32 s92, s94, s4
	s_addc_u32 s93, s95, s5
	s_add_u32 s4, s0, s4
	s_addc_u32 s5, s1, s5
	global_load_dwordx2 v[62:63], v68, s[92:93]
	s_nop 0
	global_load_dwordx2 v[68:69], v68, s[4:5]
	s_and_b64 vcc, exec, s[44:45]
	s_cbranch_vccnz .LBB0_193
	s_add_i32 s4, s37, -11
	s_cmp_ge_i32 s36, s4
	s_cbranch_scc0 .LBB0_212
; DEV void rwkv_helper(const Params& p, const Ctx& cx, int l, int unit, int lane, char* ring) {
;     ...
;   RH_LOAD(q0, 0); RH_LOAD(q1, 1); RH_LOAD(q2, 2); RH_LOAD(q3, 3); RH_LOAD(q4, 4); RH_LOAD(q5, 5); RH_LOAD(q6, 6); RH_LOAD(q7, 7);
; #pragma unroll 1
;   for (int g = 0; g < RW_NG; g += 8) {
;     RH_STEP(q0, g); RH_LOAD(q0, g + 8); __builtin_amdgcn_sched_barrier(0);
;     RH_STEP(q1, g + 1); RH_LOAD(q1, g + 9); __builtin_amdgcn_sched_barrier(0);
;     RH_STEP(q2, g + 2); RH_LOAD(q2, g + 10); __builtin_amdgcn_sched_barrier(0);
;     RH_STEP(q3, g + 3); RH_LOAD(q3, g + 11); __builtin_amdgcn_sched_barrier(0);
;     RH_STEP(q4, g + 4); RH_LOAD(q4, g + 12); __builtin_amdgcn_sched_barrier(0);
;     RH_STEP(q5, g + 5); RH_LOAD(q5, g + 13); __builtin_amdgcn_sched_barrier(0);
;     RH_STEP(q6, g + 6); RH_LOAD(q6, g + 14); __builtin_amdgcn_sched_barrier(0);
;     RH_STEP(q7, g + 7); RH_LOAD(q7, g + 15); __builtin_amdgcn_sched_barrier(0);
.LBB0_193:
	s_waitcnt vmcnt(46)
	v_cvt_f32_f16_sdwa v123, v64 dst_sel:DWORD dst_unused:UNUSED_PAD src0_sel:WORD_1
	v_cvt_f32_f16_sdwa v125, v65 dst_sel:DWORD dst_unused:UNUSED_PAD src0_sel:WORD_1
	v_cvt_f32_f16_e32 v122, v64
	v_cvt_f32_f16_e32 v124, v65
	s_waitcnt vmcnt(44)
	v_cvt_f32_f16_sdwa v127, v76 dst_sel:DWORD dst_unused:UNUSED_PAD src0_sel:WORD_1
	v_cvt_f32_f16_sdwa v133, v77 dst_sel:DWORD dst_unused:UNUSED_PAD src0_sel:WORD_1
	v_cvt_f32_f16_e32 v126, v76
	v_cvt_f32_f16_e32 v132, v77
	v_pk_fma_f32 v[76:77], v[2:3], v[124:125], v[92:93]
	v_pk_fma_f32 v[122:123], v[0:1], v[122:123], v[94:95]
	s_or_b32 s4, s37, 5
	v_pk_mul_f32 v[76:77], v[76:77], v[132:133]
	v_pk_mul_f32 v[126:127], v[122:123], v[126:127]
	v_pk_mul_f16 v123, v65, v23
	v_pk_mul_f16 v122, v64, v22
	v_cvt_pk_f16_f32 v125, v76, v77
	v_cvt_pk_f16_f32 v124, v126, v127
	ds_write_b128 v120, v[20:23] offset:12288
	ds_write_b128 v120, v[122:125] offset:13312
	s_waitcnt vmcnt(42)
	ds_write_b64 v121, v[70:71] offset:14336
	v_add_u32_e32 v181, v121, v182
	ds_write_b16 v181, v74 offset:14848
	ds_write_b16_d16_hi v181, v74 offset:14856
	ds_write_b16 v181, v75 offset:14864
	ds_write_b16_d16_hi v181, v75 offset:14872
	v_mov_b32_e32 v20, s4
	s_min_u32 s4, s37, 0x1033
	s_lshl_b32 s4, s4, 2
	s_cmp_gt_u32 s37, 51
	s_cselect_b32 s5, 0xffffff30, 48
	s_cselect_b32 s23, s10, s33
	s_cselect_b32 s92, s46, 0xfc
	s_add_i32 s93, s4, s5
	s_sub_i32 s92, s92, s93
	s_and_b64 s[4:5], s[42:43], exec
	s_cselect_b32 s4, s93, s92
	s_add_i32 s4, s4, s23
	s_ashr_i32 s5, s4, 31
	s_lshl_b64 s[4:5], s[4:5], 11
	s_add_u32 s92, s87, s4
	v_mov_b32_e32 v74, v119
	s_addc_u32 s93, s35, s5
	s_waitcnt lgkmcnt(0)
	ds_write_b32 v161, v20 offset:49152
	global_load_dwordx2 v[20:21], v74, s[92:93]
	s_add_u32 s92, s85, s4
	s_addc_u32 s93, s86, s5
	global_load_dwordx2 v[64:65], v74, s[92:93]
	s_add_u32 s92, s8, s4
	s_addc_u32 s93, s84, s5
	global_load_dwordx2 v[22:23], v74, s[92:93]
	s_add_u32 s92, s97, s4
	s_addc_u32 s93, s99, s5
	global_load_dwordx2 v[76:77], v74, s[92:93]
	s_add_u32 s92, s94, s4
	s_addc_u32 s93, s95, s5
	s_add_u32 s4, s0, s4
	s_addc_u32 s5, s1, s5
	global_load_dwordx2 v[70:71], v74, s[92:93]
	s_nop 0
	global_load_dwordx2 v[74:75], v74, s[4:5]
	s_and_b64 vcc, exec, s[44:45]
	s_cbranch_vccnz .LBB0_195
	s_add_i32 s4, s37, -10
	s_cmp_ge_i32 s36, s4
	s_cbranch_scc0 .LBB0_215
.LBB0_195:
	s_waitcnt vmcnt(46)
	v_cvt_f32_f16_sdwa v123, v72 dst_sel:DWORD dst_unused:UNUSED_PAD src0_sel:WORD_1
	v_cvt_f32_f16_sdwa v125, v73 dst_sel:DWORD dst_unused:UNUSED_PAD src0_sel:WORD_1
	v_cvt_f32_f16_e32 v122, v72
	v_cvt_f32_f16_e32 v124, v73
	s_waitcnt vmcnt(44)
	v_cvt_f32_f16_sdwa v127, v84 dst_sel:DWORD dst_unused:UNUSED_PAD src0_sel:WORD_1
	v_cvt_f32_f16_sdwa v133, v85 dst_sel:DWORD dst_unused:UNUSED_PAD src0_sel:WORD_1
	v_cvt_f32_f16_e32 v126, v84
	v_cvt_f32_f16_e32 v132, v85
	v_pk_fma_f32 v[84:85], v[2:3], v[124:125], v[92:93]
	v_pk_fma_f32 v[122:123], v[0:1], v[122:123], v[94:95]
	s_or_b32 s4, s37, 6
	v_pk_mul_f32 v[84:85], v[84:85], v[132:133]
	v_pk_mul_f32 v[126:127], v[122:123], v[126:127]
	v_pk_mul_f16 v123, v73, v27
	v_pk_mul_f16 v122, v72, v26
	v_cvt_pk_f16_f32 v125, v84, v85
	v_cvt_pk_f16_f32 v124, v126, v127
	ds_write_b128 v120, v[24:27] offset:15360
	ds_write_b128 v120, v[122:125] offset:16384
	s_waitcnt vmcnt(42)
	ds_write_b64 v121, v[78:79] offset:17408
	v_add_u32_e32 v181, v121, v182
	ds_write_b16 v181, v86 offset:17920
	ds_write_b16_d16_hi v181, v86 offset:17928
	ds_write_b16 v181, v87 offset:17936
	ds_write_b16_d16_hi v181, v87 offset:17944
	v_mov_b32_e32 v24, s4
	s_min_u32 s4, s37, 0x1032
	s_lshl_b32 s4, s4, 2
	s_cmp_gt_u32 s37, 50
	s_cselect_b32 s5, 0xffffff34, 52
	s_cselect_b32 s23, s10, s33
	s_cselect_b32 s92, s46, 0xfc
	s_add_i32 s93, s4, s5
	s_sub_i32 s92, s92, s93
	s_and_b64 s[4:5], s[42:43], exec
	s_cselect_b32 s4, s93, s92
	s_add_i32 s4, s4, s23
	s_ashr_i32 s5, s4, 31
	s_lshl_b64 s[4:5], s[4:5], 11
	s_add_u32 s92, s87, s4
	v_mov_b32_e32 v86, v119
	s_addc_u32 s93, s35, s5
	s_waitcnt lgkmcnt(0)
	ds_write_b32 v161, v24 offset:49152
	global_load_dwordx2 v[24:25], v86, s[92:93]
	s_add_u32 s92, s85, s4
	s_addc_u32 s93, s86, s5
	global_load_dwordx2 v[72:73], v86, s[92:93]
	s_add_u32 s92, s8, s4
	s_addc_u32 s93, s84, s5
	global_load_dwordx2 v[26:27], v86, s[92:93]
	s_add_u32 s92, s97, s4
	s_addc_u32 s93, s99, s5
	global_load_dwordx2 v[84:85], v86, s[92:93]
	s_add_u32 s92, s94, s4
	s_addc_u32 s93, s95, s5
	s_add_u32 s4, s0, s4
	s_addc_u32 s5, s1, s5
	global_load_dwordx2 v[78:79], v86, s[92:93]
	s_nop 0
	global_load_dwordx2 v[86:87], v86, s[4:5]
	s_and_b64 vcc, exec, s[44:45]
	s_cbranch_vccnz .LBB0_197
	s_add_i32 s4, s37, -9
	s_cmp_ge_i32 s36, s4
	s_cbranch_scc0 .LBB0_218
; DEV void rwkv_helper(const Params& p, const Ctx& cx, int l, int unit, int lane, char* ring) {
;     ...
;   RH_LOAD(q0, 0); RH_LOAD(q1, 1); RH_LOAD(q2, 2); RH_LOAD(q3, 3); RH_LOAD(q4, 4); RH_LOAD(q5, 5); RH_LOAD(q6, 6); RH_LOAD(q7, 7);
; #pragma unroll 1
;   for (int g = 0; g < RW_NG; g += 8) {
;     RH_STEP(q0, g); RH_LOAD(q0, g + 8); __builtin_amdgcn_sched_barrier(0);
;     RH_STEP(q1, g + 1); RH_LOAD(q1, g + 9); __builtin_amdgcn_sched_barrier(0);
;     RH_STEP(q2, g + 2); RH_LOAD(q2, g + 10); __builtin_amdgcn_sched_barrier(0);
;     RH_STEP(q3, g + 3); RH_LOAD(q3, g + 11); __builtin_amdgcn_sched_barrier(0);
;     RH_STEP(q4, g + 4); RH_LOAD(q4, g + 12); __builtin_amdgcn_sched_barrier(0);
;     RH_STEP(q5, g + 5); RH_LOAD(q5, g + 13); __builtin_amdgcn_sched_barrier(0);
;     RH_STEP(q6, g + 6); RH_LOAD(q6, g + 14); __builtin_amdgcn_sched_barrier(0);
;     RH_STEP(q7, g + 7); RH_LOAD(q7, g + 15); __builtin_amdgcn_sched_barrier(0);
.LBB0_197:
	s_waitcnt vmcnt(46)
	v_cvt_f32_f16_sdwa v123, v82 dst_sel:DWORD dst_unused:UNUSED_PAD src0_sel:WORD_1
	v_cvt_f32_f16_sdwa v125, v83 dst_sel:DWORD dst_unused:UNUSED_PAD src0_sel:WORD_1
	v_cvt_f32_f16_e32 v122, v82
	v_cvt_f32_f16_e32 v124, v83
	s_waitcnt vmcnt(44)
	v_cvt_f32_f16_sdwa v127, v98 dst_sel:DWORD dst_unused:UNUSED_PAD src0_sel:WORD_1
	v_cvt_f32_f16_sdwa v133, v99 dst_sel:DWORD dst_unused:UNUSED_PAD src0_sel:WORD_1
	v_cvt_f32_f16_e32 v126, v98
	v_cvt_f32_f16_e32 v132, v99
	v_pk_fma_f32 v[98:99], v[2:3], v[124:125], v[92:93]
	v_pk_fma_f32 v[122:123], v[0:1], v[122:123], v[94:95]
	s_or_b32 s4, s37, 7
	v_pk_mul_f32 v[98:99], v[98:99], v[132:133]
	v_pk_mul_f32 v[126:127], v[122:123], v[126:127]
	v_pk_mul_f16 v123, v83, v31
	v_pk_mul_f16 v122, v82, v30
	v_cvt_pk_f16_f32 v125, v98, v99
	v_cvt_pk_f16_f32 v124, v126, v127
	ds_write_b128 v120, v[28:31] offset:18432
	ds_write_b128 v120, v[122:125] offset:19456
	s_waitcnt vmcnt(42)
	ds_write_b64 v121, v[88:89] offset:20480
	v_add_u32_e32 v181, v121, v182
	ds_write_b16 v181, v96 offset:20992
	ds_write_b16_d16_hi v181, v96 offset:21000
	ds_write_b16 v181, v97 offset:21008
	ds_write_b16_d16_hi v181, v97 offset:21016
	v_mov_b32_e32 v28, s4
	s_min_u32 s4, s37, 0x1031
	s_lshl_b32 s4, s4, 2
	s_cmp_gt_u32 s37, 49
	s_cselect_b32 s5, 0xffffff38, 56
	s_cselect_b32 s23, s10, s33
	s_cselect_b32 s92, s46, 0xfc
	s_add_i32 s93, s4, s5
	s_sub_i32 s92, s92, s93
	s_and_b64 s[4:5], s[42:43], exec
	s_cselect_b32 s4, s93, s92
	s_add_i32 s4, s4, s23
	s_ashr_i32 s5, s4, 31
	s_lshl_b64 s[4:5], s[4:5], 11
	s_add_u32 s92, s87, s4
	v_mov_b32_e32 v96, v119
	s_addc_u32 s93, s35, s5
	s_waitcnt lgkmcnt(0)
	ds_write_b32 v161, v28 offset:49152
	global_load_dwordx2 v[28:29], v96, s[92:93]
	s_add_u32 s92, s85, s4
	s_addc_u32 s93, s86, s5
	global_load_dwordx2 v[82:83], v96, s[92:93]
	s_add_u32 s92, s8, s4
	s_addc_u32 s93, s84, s5
	global_load_dwordx2 v[30:31], v96, s[92:93]
	s_add_u32 s92, s97, s4
	s_addc_u32 s93, s99, s5
	global_load_dwordx2 v[98:99], v96, s[92:93]
	s_add_u32 s92, s94, s4
	s_addc_u32 s93, s95, s5
	s_add_u32 s4, s0, s4
	s_addc_u32 s5, s1, s5
	global_load_dwordx2 v[88:89], v96, s[92:93]
	s_nop 0
	global_load_dwordx2 v[96:97], v96, s[4:5]
	s_and_b64 vcc, exec, s[44:45]
	s_cbranch_vccnz .LBB0_182
	s_add_i32 s4, s37, -8
	s_cmp_ge_i32 s36, s4
	s_cbranch_scc0 .LBB0_221
	s_branch .LBB0_182

; #define LAS3 __attribute__((address_space(3)))
; #define RC_WAIT(gq) { if (pseen <= (gq)) { do { pseen = __builtin_amdgcn_readfirstlane(*pflag); if (pseen <= (gq)) __builtin_amdgcn_s_sleep(1); } while (pseen <= (gq)); } asm volatile("" ::: "memory"); }
; DEV void rwkv_consumer(const Params& p, const Ctx& cx, int l, int task, int lane, const char* ring, int widx) {
;   const int unit = task >> 4, d = unit & 1, h = (unit >> 1) & 15, b = unit >> 5;
;   const int j = lane >> 4, s = lane & 15;
;   const int myrow = (task & 15) * 4 + j;
;   char* pO = (char*)((h16*)(p.ws + OFF_REG2) + (size_t)d * ARR + h * 64);
;   const int sm = d ? 3 - (s & 3) : (s & 3);
;   const unsigned vov0 = (unsigned)(sm * 2048 + myrow * 2);
;   const unsigned rofs = (unsigned)(s * 8);
;   const unsigned vrofs = (unsigned)(2560 + myrow * 2);
;   LAS3 volatile int* pflag = (LAS3 volatile int*)(ring + RW_FLAGS);
;   LAS3 volatile int* cflag = (LAS3 volatile int*)(ring + RW_FLAGS + 64) + widx;
;   float S0 = 0.f, S1 = 0.f, S2 = 0.f, S3 = 0.f;
;   int pseen = 0;
;   struct GD { u2v w[4], kk[4], kka[4], kd[4], r[4]; unsigned v[4]; };
;   GD A, B;
;     ...
;   RC_WAIT(0); RC_LOAD(A, 0);
.LBB0_229:
	s_ashr_i32 s4, s31, 4
	s_lshl_b32 s1, s34, 4
	s_and_b32 s4, s4, -4
	s_or_b32 s1, s1, s4
	s_or_b32 s4, s1, s50
	s_lshl_b32 s1, s4, 2
	v_and_or_b32 v0, s1, 60, v107
	s_waitcnt vmcnt(0)
	v_lshlrev_b32_e32 v82, 1, v0
	v_lshlrev_b32_e32 v184, 3, v0
	v_add_u32_e32 v0, 16, v116
	v_add_u32_e32 v36, 16, v117
	v_add_u32_e32 v20, 0x800, v0
	v_add_u32_e32 v41, 16, v184
	ds_read2_b64 v[0:3], v20 offset1:16
	ds_read_b128 v[4:7], v36
	ds_read_b128 v[8:11], v36 offset:256
	ds_read_b128 v[12:15], v36 offset:1024
	ds_read_b128 v[16:19], v36 offset:1280
	ds_read2_b64 v[20:23], v20 offset0:32 offset1:48
	ds_read_b128 v[24:27], v36 offset:512
	s_waitcnt vmcnt(9)
	ds_read_b128 v[28:31], v36 offset:768
	s_waitcnt vmcnt(3)
	ds_read_b128 v[32:35], v36 offset:1536
	ds_read_b128 v[36:39], v36 offset:1792
	ds_read_b64 v[88:89], v41 offset:2560
	s_bfe_u32 s5, s4, 0x10004
	s_mul_i32 s8, s5, 0x4100000
	s_add_u32 s8, s20, s8
	s_addc_u32 s10, s21, 0
	s_and_b32 s1, s1, 0x780
	s_add_u32 s1, s8, s1
	s_addc_u32 s8, s10, 0
	s_cmp_eq_u32 s5, 0
	s_cselect_b64 s[42:43], -1, 0
	s_ashr_i32 s4, s4, 9
	v_cndmask_b32_e64 v40, v115, v114, s[42:43]
	s_lshl_b32 s22, s4, 8
	s_mov_b32 s33, 0
	v_or_b32_e32 v83, v40, v82
	s_lshl_b32 s10, s4, 14
	s_add_i32 s22, s22, 0x8000
	v_mov_b32_e32 v84, 0
	v_mov_b32_e32 v85, 0
	v_mov_b32_e32 v86, 0
	v_mov_b32_e32 v87, 0
	s_waitcnt vmcnt(0)
	s_and_b64 s[4:5], s[42:43], exec
	s_cselect_b32 s4, 0, 0xfc
	s_add_i32 s4, s22, s4
	s_lshl_b32 s4, s4, 11
	s_add_u32 s36, s1, s4
	s_addc_u32 s37, s8, 0
	s_and_b64 s[4:5], s[42:43], exec
	s_cselect_b32 s4, 0, 0x3ffc
	s_add_i32 s4, s10, s4
	s_lshl_b32 s4, s4, 11
	s_add_u32 s88, s1, s4
	s_addc_u32 s89, s8, 0
	s_and_b64 s[4:5], s[42:43], exec
	s_mov_b32 s44, 0xffffe000
	s_and_b64 s[4:5], s[42:43], exec
	s_cselect_b32 s44, 0x2000, s44
	s_cselect_b32 s45, 0, -1
	v_mov_b32_e32 v172, s9
	v_add_u32_e32 v177, 0x800, v116
	s_movk_i32 s4, 0xc10
	v_add_u32_e32 v178, s4, v177
	v_add_u32_e32 v179, s4, v117
	v_add_u32_e32 v180, s4, v184
	s_branch .Lc_top

; #define RC_WAIT(gq) { if (pseen <= (gq)) { do { pseen = __builtin_amdgcn_readfirstlane(*pflag); if (pseen <= (gq)) __builtin_amdgcn_s_sleep(1); } while (pseen <= (gq)); } asm volatile("" ::: "memory"); }
; DEV void rwkv_consumer(const Params& p, const Ctx& cx, int l, int task, int lane, const char* ring, int widx) {
;     ...
;     RC_WAIT(g + 1); RC_LOAD(B, g + 1);
.Lc_h1:
	ds_read2_b64 v[56:59], v178 offset1:16
	ds_read_b128 v[72:75], v179
	ds_read_b128 v[64:67], v179 offset:256
	ds_read_b128 v[76:79], v179 offset:1024
	ds_read_b128 v[68:71], v179 offset:1280
	ds_read2_b64 v[40:43], v178 offset0:32 offset1:48
	ds_read_b128 v[52:55], v179 offset:512
	ds_read_b128 v[44:47], v179 offset:768
	s_waitcnt lgkmcnt(8)
	v_fma_mix_f32 v98, v84, v6, 0 op_sel:[0,0,0] op_sel_hi:[0,1,0]
	ds_read_b128 v[60:63], v179 offset:1536
	v_fma_mix_f32 v98, v85, v6, v98 op_sel:[0,1,0] op_sel_hi:[0,1,0]
	ds_read_b128 v[48:51], v179 offset:1792
	v_fma_mix_f32 v98, v86, v7, v98 op_sel:[0,0,0] op_sel_hi:[0,1,0]
	ds_read_b64 v[92:93], v180 offset:2560
	v_fma_mix_f32 v98, v87, v7, v98 op_sel:[0,1,0] op_sel_hi:[0,1,0]
	v_fma_mix_f32 v100, v88, v14, 0 op_sel:[0,0,0] op_sel_hi:[1,1,0]
	v_fma_mix_f32 v101, v88, v14, 0 op_sel:[0,1,0] op_sel_hi:[1,1,0]
	v_add_f32_dpp v98, v98, v98 quad_perm:[1,0,3,2] row_mask:0xf bank_mask:0xf bound_ctrl:1
	v_fma_mix_f32 v102, v88, v15, 0 op_sel:[0,0,0] op_sel_hi:[1,1,0]
	v_fma_mix_f32 v103, v88, v15, 0 op_sel:[0,1,0] op_sel_hi:[1,1,0]
	v_add_f32_dpp v98, v98, v98 quad_perm:[2,3,0,1] row_mask:0xf bank_mask:0xf bound_ctrl:1
	v_fma_mix_f32 v84, v84, v4, v100 op_sel:[0,0,0] op_sel_hi:[0,1,0]
	v_fma_mix_f32 v85, v85, v4, v101 op_sel:[0,1,0] op_sel_hi:[0,1,0]
	v_add_f32_dpp v98, v98, v98 row_half_mirror row_mask:0xf bank_mask:0xf bound_ctrl:1
	v_fma_mix_f32 v86, v86, v5, v102 op_sel:[0,0,0] op_sel_hi:[0,1,0]
	v_fma_mix_f32 v87, v87, v5, v103 op_sel:[0,1,0] op_sel_hi:[0,1,0]
	v_add_f32_dpp v98, v98, v98 row_mirror row_mask:0xf bank_mask:0xf bound_ctrl:1
	v_fma_mix_f32 v84, -v98, v12, v84 op_sel:[0,0,0] op_sel_hi:[0,1,0]
	v_fma_mix_f32 v85, -v98, v12, v85 op_sel:[0,1,0] op_sel_hi:[0,1,0]
	v_fma_mix_f32 v86, -v98, v13, v86 op_sel:[0,0,0] op_sel_hi:[0,1,0]
	v_fma_mix_f32 v87, -v98, v13, v87 op_sel:[0,1,0] op_sel_hi:[0,1,0]
	v_fma_mix_f32 v99, v84, v10, 0 op_sel:[0,0,0] op_sel_hi:[0,1,0]
	v_fma_mix_f32 v96, v84, v0, 0 op_sel:[0,0,0] op_sel_hi:[0,1,0]
	v_fma_mix_f32 v99, v85, v10, v99 op_sel:[0,1,0] op_sel_hi:[0,1,0]
	v_fma_mix_f32 v96, v85, v0, v96 op_sel:[0,1,0] op_sel_hi:[0,1,0]
	v_fma_mix_f32 v99, v86, v11, v99 op_sel:[0,0,0] op_sel_hi:[0,1,0]
	v_fma_mix_f32 v96, v86, v1, v96 op_sel:[0,0,0] op_sel_hi:[0,1,0]
	v_fma_mix_f32 v99, v87, v11, v99 op_sel:[0,1,0] op_sel_hi:[0,1,0]
	v_fma_mix_f32 v96, v87, v1, v96 op_sel:[0,1,0] op_sel_hi:[0,1,0]
	v_fma_mix_f32 v101, v88, v18, 0 op_sel:[1,0,0] op_sel_hi:[1,1,0]
	v_fma_mix_f32 v102, v88, v18, 0 op_sel:[1,1,0] op_sel_hi:[1,1,0]
	v_add_f32_dpp v99, v99, v99 quad_perm:[1,0,3,2] row_mask:0xf bank_mask:0xf bound_ctrl:1
	v_fma_mix_f32 v103, v88, v19, 0 op_sel:[1,0,0] op_sel_hi:[1,1,0]
	v_fma_mix_f32 v104, v88, v19, 0 op_sel:[1,1,0] op_sel_hi:[1,1,0]
	v_add_f32_dpp v99, v99, v99 quad_perm:[2,3,0,1] row_mask:0xf bank_mask:0xf bound_ctrl:1
	v_fma_mix_f32 v84, v84, v8, v101 op_sel:[0,0,0] op_sel_hi:[0,1,0]
	v_fma_mix_f32 v85, v85, v8, v102 op_sel:[0,1,0] op_sel_hi:[0,1,0]
	v_add_f32_dpp v99, v99, v99 row_half_mirror row_mask:0xf bank_mask:0xf bound_ctrl:1
	v_fma_mix_f32 v86, v86, v9, v103 op_sel:[0,0,0] op_sel_hi:[0,1,0]
	v_fma_mix_f32 v87, v87, v9, v104 op_sel:[0,1,0] op_sel_hi:[0,1,0]
	v_add_f32_dpp v99, v99, v99 row_mirror row_mask:0xf bank_mask:0xf bound_ctrl:1
	v_fma_mix_f32 v84, -v99, v16, v84 op_sel:[0,0,0] op_sel_hi:[0,1,0]
	v_fma_mix_f32 v85, -v99, v16, v85 op_sel:[0,1,0] op_sel_hi:[0,1,0]
	v_fma_mix_f32 v86, -v99, v17, v86 op_sel:[0,0,0] op_sel_hi:[0,1,0]
	v_fma_mix_f32 v87, -v99, v17, v87 op_sel:[0,1,0] op_sel_hi:[0,1,0]
	v_fma_mix_f32 v100, v84, v26, 0 op_sel:[0,0,0] op_sel_hi:[0,1,0]
	v_fma_mix_f32 v97, v84, v2, 0 op_sel:[0,0,0] op_sel_hi:[0,1,0]
	v_fma_mix_f32 v100, v85, v26, v100 op_sel:[0,1,0] op_sel_hi:[0,1,0]
	v_fma_mix_f32 v97, v85, v2, v97 op_sel:[0,1,0] op_sel_hi:[0,1,0]
	v_fma_mix_f32 v100, v86, v27, v100 op_sel:[0,0,0] op_sel_hi:[0,1,0]
	v_fma_mix_f32 v97, v86, v3, v97 op_sel:[0,0,0] op_sel_hi:[0,1,0]
	v_fma_mix_f32 v100, v87, v27, v100 op_sel:[0,1,0] op_sel_hi:[0,1,0]
	v_fma_mix_f32 v97, v87, v3, v97 op_sel:[0,1,0] op_sel_hi:[0,1,0]
	v_fma_mix_f32 v102, v89, v34, 0 op_sel:[0,0,0] op_sel_hi:[1,1,0]
	v_fma_mix_f32 v103, v89, v34, 0 op_sel:[0,1,0] op_sel_hi:[1,1,0]
	v_add_f32_dpp v100, v100, v100 quad_perm:[1,0,3,2] row_mask:0xf bank_mask:0xf bound_ctrl:1
	v_fma_mix_f32 v104, v89, v35, 0 op_sel:[0,0,0] op_sel_hi:[1,1,0]
	v_fma_mix_f32 v105, v89, v35, 0 op_sel:[0,1,0] op_sel_hi:[1,1,0]
	v_add_f32_dpp v100, v100, v100 quad_perm:[2,3,0,1] row_mask:0xf bank_mask:0xf bound_ctrl:1
	v_fma_mix_f32 v84, v84, v24, v102 op_sel:[0,0,0] op_sel_hi:[0,1,0]
	v_fma_mix_f32 v85, v85, v24, v103 op_sel:[0,1,0] op_sel_hi:[0,1,0]
	v_add_f32_dpp v100, v100, v100 row_half_mirror row_mask:0xf bank_mask:0xf bound_ctrl:1
	v_fma_mix_f32 v86, v86, v25, v104 op_sel:[0,0,0] op_sel_hi:[0,1,0]
	v_fma_mix_f32 v87, v87, v25, v105 op_sel:[0,1,0] op_sel_hi:[0,1,0]
	v_add_f32_dpp v100, v100, v100 row_mirror row_mask:0xf bank_mask:0xf bound_ctrl:1
	v_fma_mix_f32 v84, -v100, v32, v84 op_sel:[0,0,0] op_sel_hi:[0,1,0]
	v_fma_mix_f32 v85, -v100, v32, v85 op_sel:[0,1,0] op_sel_hi:[0,1,0]
	v_fma_mix_f32 v86, -v100, v33, v86 op_sel:[0,0,0] op_sel_hi:[0,1,0]
	v_fma_mix_f32 v87, -v100, v33, v87 op_sel:[0,1,0] op_sel_hi:[0,1,0]
	v_fma_mix_f32 v101, v84, v30, 0 op_sel:[0,0,0] op_sel_hi:[0,1,0]
	v_fma_mix_f32 v98, v84, v20, 0 op_sel:[0,0,0] op_sel_hi:[0,1,0]
	v_fma_mix_f32 v101, v85, v30, v101 op_sel:[0,1,0] op_sel_hi:[0,1,0]
	v_fma_mix_f32 v98, v85, v20, v98 op_sel:[0,1,0] op_sel_hi:[0,1,0]
	v_fma_mix_f32 v101, v86, v31, v101 op_sel:[0,0,0] op_sel_hi:[0,1,0]
	v_fma_mix_f32 v98, v86, v21, v98 op_sel:[0,0,0] op_sel_hi:[0,1,0]
; #define RC_WAIT(gq) { if (pseen <= (gq)) { do { pseen = __builtin_amdgcn_readfirstlane(*pflag); if (pseen <= (gq)) __builtin_amdgcn_s_sleep(1); } while (pseen <= (gq)); } asm volatile("" ::: "memory"); }
; DEV void rwkv_consumer(const Params& p, const Ctx& cx, int l, int task, int lane, const char* ring, int widx) {
;     ...
;   RC_WAIT(0); RC_LOAD(A, 0);
; #pragma unroll 1
;   for (int g = 0; g < RW_NG; g += 2) {
;     RC_WAIT(g + 1); RC_LOAD(B, g + 1);
;     RC_COMP(A, g);
;     if (g + 2 < RW_NG) { RC_WAIT(g + 2); RC_LOAD(A, g + 2); }
	v_fma_mix_f32 v101, v87, v31, v101 op_sel:[0,1,0] op_sel_hi:[0,1,0]
	v_fma_mix_f32 v98, v87, v21, v98 op_sel:[0,1,0] op_sel_hi:[0,1,0]
	v_fma_mix_f32 v103, v89, v38, 0 op_sel:[1,0,0] op_sel_hi:[1,1,0]
	v_fma_mix_f32 v104, v89, v38, 0 op_sel:[1,1,0] op_sel_hi:[1,1,0]
	v_add_f32_dpp v101, v101, v101 quad_perm:[1,0,3,2] row_mask:0xf bank_mask:0xf bound_ctrl:1
	v_fma_mix_f32 v105, v89, v39, 0 op_sel:[1,0,0] op_sel_hi:[1,1,0]
	v_fma_mix_f32 v119, v89, v39, 0 op_sel:[1,1,0] op_sel_hi:[1,1,0]
	v_add_f32_dpp v101, v101, v101 quad_perm:[2,3,0,1] row_mask:0xf bank_mask:0xf bound_ctrl:1
	v_fma_mix_f32 v84, v84, v28, v103 op_sel:[0,0,0] op_sel_hi:[0,1,0]
	v_fma_mix_f32 v85, v85, v28, v104 op_sel:[0,1,0] op_sel_hi:[0,1,0]
	v_add_f32_dpp v101, v101, v101 row_half_mirror row_mask:0xf bank_mask:0xf bound_ctrl:1
	v_fma_mix_f32 v86, v86, v29, v105 op_sel:[0,0,0] op_sel_hi:[0,1,0]
	v_fma_mix_f32 v87, v87, v29, v119 op_sel:[0,1,0] op_sel_hi:[0,1,0]
	v_add_f32_dpp v101, v101, v101 row_mirror row_mask:0xf bank_mask:0xf bound_ctrl:1
	v_fma_mix_f32 v84, -v101, v36, v84 op_sel:[0,0,0] op_sel_hi:[0,1,0]
	v_fma_mix_f32 v85, -v101, v36, v85 op_sel:[0,1,0] op_sel_hi:[0,1,0]
	v_fma_mix_f32 v86, -v101, v37, v86 op_sel:[0,0,0] op_sel_hi:[0,1,0]
	v_fma_mix_f32 v87, -v101, v37, v87 op_sel:[0,1,0] op_sel_hi:[0,1,0]
	v_fma_mix_f32 v99, v84, v22, 0 op_sel:[0,0,0] op_sel_hi:[0,1,0]
	v_fma_mix_f32 v99, v85, v22, v99 op_sel:[0,1,0] op_sel_hi:[0,1,0]
	v_fma_mix_f32 v99, v86, v23, v99 op_sel:[0,0,0] op_sel_hi:[0,1,0]
	v_fma_mix_f32 v99, v87, v23, v99 op_sel:[0,1,0] op_sel_hi:[0,1,0]
	v_cndmask_b32_e64 v101, v97, v96, s[38:39]
	v_cndmask_b32_e64 v96, v96, v97, s[38:39]
	v_cndmask_b32_e64 v97, v99, v98, s[38:39]
	v_cndmask_b32_e64 v98, v98, v99, s[38:39]
	s_add_i32 s34, s33, 2
	v_add_f32_dpp v96, v96, v101 quad_perm:[1,0,3,2] row_mask:0xf bank_mask:0xf bound_ctrl:1
	s_and_b32 s4, s34, 14
	s_mulk_i32 s4, 0xc00
	v_add_f32_dpp v97, v98, v97 quad_perm:[1,0,3,2] row_mask:0xf bank_mask:0xf bound_ctrl:1
	s_add_i32 s4, s4, 16
	v_cndmask_b32_e64 v98, v97, v96, s[40:41]
	v_cndmask_b32_e64 v96, v96, v97, s[40:41]
	v_add_u32_e32 v174, s4, v177
	v_add_u32_e32 v175, s4, v117
	v_add_f32_dpp v96, v96, v98 quad_perm:[2,3,0,1] row_mask:0xf bank_mask:0xf bound_ctrl:1
	v_add_u32_e32 v176, s4, v184
	v_mov_b32_e32 v173, s23
	v_add_f32_dpp v96, v96, v96 row_ror:4 row_mask:0xf bank_mask:0xf bound_ctrl:1
	ds_write_b32 v172, v173 offset:49216
	s_nop 0
	v_add_f32_dpp v96, v96, v96 row_ror:8 row_mask:0xf bank_mask:0xf bound_ctrl:1
	v_cvt_f16_f32_e32 v96, v96
	global_store_short v83, v96, s[36:37]
	s_add_u32 s36, s36, s44
	s_addc_u32 s37, s37, s45
	s_cmpk_gt_u32 s33, 0x103d
	s_cbranch_scc1 .Lc_last
	s_cmp_gt_i32 s0, s34
	s_cbranch_scc0 .Lc_poll2
.Lc_ld2:
	ds_read2_b64 v[0:3], v174 offset1:16
	ds_read_b128 v[4:7], v175
	ds_read_b128 v[8:11], v175 offset:256
	ds_read_b128 v[12:15], v175 offset:1024
	ds_read_b128 v[16:19], v175 offset:1280
	ds_read2_b64 v[20:23], v174 offset0:32 offset1:48
	ds_read_b128 v[24:27], v175 offset:512
	ds_read_b128 v[28:31], v175 offset:768
	ds_read_b128 v[32:35], v175 offset:1536
	ds_read_b128 v[36:39], v175 offset:1792
	ds_read_b64 v[88:89], v176 offset:2560
	s_waitcnt lgkmcnt(11)
.Lc_h2:
	v_fma_mix_f32 v98, v84, v74, 0 op_sel:[0,0,0] op_sel_hi:[0,1,0]
	v_fma_mix_f32 v98, v85, v74, v98 op_sel:[0,1,0] op_sel_hi:[0,1,0]
	v_fma_mix_f32 v98, v86, v75, v98 op_sel:[0,0,0] op_sel_hi:[0,1,0]
	v_fma_mix_f32 v98, v87, v75, v98 op_sel:[0,1,0] op_sel_hi:[0,1,0]
	v_fma_mix_f32 v100, v92, v78, 0 op_sel:[0,0,0] op_sel_hi:[1,1,0]
	v_fma_mix_f32 v101, v92, v78, 0 op_sel:[0,1,0] op_sel_hi:[1,1,0]
	v_add_f32_dpp v98, v98, v98 quad_perm:[1,0,3,2] row_mask:0xf bank_mask:0xf bound_ctrl:1
	v_fma_mix_f32 v102, v92, v79, 0 op_sel:[0,0,0] op_sel_hi:[1,1,0]
	v_fma_mix_f32 v103, v92, v79, 0 op_sel:[0,1,0] op_sel_hi:[1,1,0]
	v_add_f32_dpp v98, v98, v98 quad_perm:[2,3,0,1] row_mask:0xf bank_mask:0xf bound_ctrl:1
	v_fma_mix_f32 v84, v84, v72, v100 op_sel:[0,0,0] op_sel_hi:[0,1,0]
	v_fma_mix_f32 v85, v85, v72, v101 op_sel:[0,1,0] op_sel_hi:[0,1,0]
	v_add_f32_dpp v98, v98, v98 row_half_mirror row_mask:0xf bank_mask:0xf bound_ctrl:1
	v_fma_mix_f32 v86, v86, v73, v102 op_sel:[0,0,0] op_sel_hi:[0,1,0]
	v_fma_mix_f32 v87, v87, v73, v103 op_sel:[0,1,0] op_sel_hi:[0,1,0]
	v_add_f32_dpp v98, v98, v98 row_mirror row_mask:0xf bank_mask:0xf bound_ctrl:1
	v_fma_mix_f32 v84, -v98, v76, v84 op_sel:[0,0,0] op_sel_hi:[0,1,0]
	v_fma_mix_f32 v85, -v98, v76, v85 op_sel:[0,1,0] op_sel_hi:[0,1,0]
	v_fma_mix_f32 v86, -v98, v77, v86 op_sel:[0,0,0] op_sel_hi:[0,1,0]
	v_fma_mix_f32 v87, -v98, v77, v87 op_sel:[0,1,0] op_sel_hi:[0,1,0]
	v_fma_mix_f32 v73, v84, v66, 0 op_sel:[0,0,0] op_sel_hi:[0,1,0]
	v_fma_mix_f32 v97, v84, v56, 0 op_sel:[0,0,0] op_sel_hi:[0,1,0]
	v_fma_mix_f32 v73, v85, v66, v73 op_sel:[0,1,0] op_sel_hi:[0,1,0]
	v_fma_mix_f32 v56, v85, v56, v97 op_sel:[0,1,0] op_sel_hi:[0,1,0]
	v_fma_mix_f32 v73, v86, v67, v73 op_sel:[0,0,0] op_sel_hi:[0,1,0]
	v_fma_mix_f32 v56, v86, v57, v56 op_sel:[0,0,0] op_sel_hi:[0,1,0]
	v_fma_mix_f32 v73, v87, v67, v73 op_sel:[0,1,0] op_sel_hi:[0,1,0]
	v_fma_mix_f32 v56, v87, v57, v56 op_sel:[0,1,0] op_sel_hi:[0,1,0]
	v_fma_mix_f32 v75, v92, v70, 0 op_sel:[1,0,0] op_sel_hi:[1,1,0]
	v_fma_mix_f32 v76, v92, v70, 0 op_sel:[1,1,0] op_sel_hi:[1,1,0]
	v_add_f32_dpp v73, v73, v73 quad_perm:[1,0,3,2] row_mask:0xf bank_mask:0xf bound_ctrl:1
	v_fma_mix_f32 v77, v92, v71, 0 op_sel:[1,0,0] op_sel_hi:[1,1,0]
	v_fma_mix_f32 v78, v92, v71, 0 op_sel:[1,1,0] op_sel_hi:[1,1,0]
	v_add_f32_dpp v73, v73, v73 quad_perm:[2,3,0,1] row_mask:0xf bank_mask:0xf bound_ctrl:1
	v_fma_mix_f32 v84, v84, v64, v75 op_sel:[0,0,0] op_sel_hi:[0,1,0]
	v_fma_mix_f32 v85, v85, v64, v76 op_sel:[0,1,0] op_sel_hi:[0,1,0]
	v_add_f32_dpp v73, v73, v73 row_half_mirror row_mask:0xf bank_mask:0xf bound_ctrl:1
	v_fma_mix_f32 v86, v86, v65, v77 op_sel:[0,0,0] op_sel_hi:[0,1,0]
	v_fma_mix_f32 v87, v87, v65, v78 op_sel:[0,1,0] op_sel_hi:[0,1,0]
	v_add_f32_dpp v73, v73, v73 row_mirror row_mask:0xf bank_mask:0xf bound_ctrl:1
	v_fma_mix_f32 v84, -v73, v68, v84 op_sel:[0,0,0] op_sel_hi:[0,1,0]
	v_fma_mix_f32 v85, -v73, v68, v85 op_sel:[0,1,0] op_sel_hi:[0,1,0]
	v_fma_mix_f32 v86, -v73, v69, v86 op_sel:[0,0,0] op_sel_hi:[0,1,0]
	v_fma_mix_f32 v87, -v73, v69, v87 op_sel:[0,1,0] op_sel_hi:[0,1,0]
	v_fma_mix_f32 v64, v84, v54, 0 op_sel:[0,0,0] op_sel_hi:[0,1,0]
	v_fma_mix_f32 v57, v84, v58, 0 op_sel:[0,0,0] op_sel_hi:[0,1,0]
	v_fma_mix_f32 v64, v85, v54, v64 op_sel:[0,1,0] op_sel_hi:[0,1,0]
	v_fma_mix_f32 v57, v85, v58, v57 op_sel:[0,1,0] op_sel_hi:[0,1,0]
	v_fma_mix_f32 v64, v86, v55, v64 op_sel:[0,0,0] op_sel_hi:[0,1,0]
	v_fma_mix_f32 v57, v86, v59, v57 op_sel:[0,0,0] op_sel_hi:[0,1,0]
	v_fma_mix_f32 v64, v87, v55, v64 op_sel:[0,1,0] op_sel_hi:[0,1,0]
	v_fma_mix_f32 v57, v87, v59, v57 op_sel:[0,1,0] op_sel_hi:[0,1,0]
	v_fma_mix_f32 v66, v93, v62, 0 op_sel:[0,0,0] op_sel_hi:[1,1,0]
	v_fma_mix_f32 v67, v93, v62, 0 op_sel:[0,1,0] op_sel_hi:[1,1,0]
	v_add_f32_dpp v64, v64, v64 quad_perm:[1,0,3,2] row_mask:0xf bank_mask:0xf bound_ctrl:1
	v_fma_mix_f32 v68, v93, v63, 0 op_sel:[0,0,0] op_sel_hi:[1,1,0]
	v_fma_mix_f32 v69, v93, v63, 0 op_sel:[0,1,0] op_sel_hi:[1,1,0]
	v_add_f32_dpp v64, v64, v64 quad_perm:[2,3,0,1] row_mask:0xf bank_mask:0xf bound_ctrl:1
	v_fma_mix_f32 v84, v84, v52, v66 op_sel:[0,0,0] op_sel_hi:[0,1,0]
	v_fma_mix_f32 v85, v85, v52, v67 op_sel:[0,1,0] op_sel_hi:[0,1,0]
	v_add_f32_dpp v64, v64, v64 row_half_mirror row_mask:0xf bank_mask:0xf bound_ctrl:1
	v_fma_mix_f32 v86, v86, v53, v68 op_sel:[0,0,0] op_sel_hi:[0,1,0]
	v_fma_mix_f32 v87, v87, v53, v69 op_sel:[0,1,0] op_sel_hi:[0,1,0]
	v_add_f32_dpp v64, v64, v64 row_mirror row_mask:0xf bank_mask:0xf bound_ctrl:1
	v_fma_mix_f32 v84, -v64, v60, v84 op_sel:[0,0,0] op_sel_hi:[0,1,0]
	v_fma_mix_f32 v85, -v64, v60, v85 op_sel:[0,1,0] op_sel_hi:[0,1,0]
	v_fma_mix_f32 v86, -v64, v61, v86 op_sel:[0,0,0] op_sel_hi:[0,1,0]
	v_fma_mix_f32 v87, -v64, v61, v87 op_sel:[0,1,0] op_sel_hi:[0,1,0]
	v_fma_mix_f32 v53, v84, v46, 0 op_sel:[0,0,0] op_sel_hi:[0,1,0]
	v_fma_mix_f32 v59, v84, v40, 0 op_sel:[0,0,0] op_sel_hi:[0,1,0]
	v_fma_mix_f32 v53, v85, v46, v53 op_sel:[0,1,0] op_sel_hi:[0,1,0]
	v_fma_mix_f32 v40, v85, v40, v59 op_sel:[0,1,0] op_sel_hi:[0,1,0]
	v_fma_mix_f32 v53, v86, v47, v53 op_sel:[0,0,0] op_sel_hi:[0,1,0]
	v_fma_mix_f32 v40, v86, v41, v40 op_sel:[0,0,0] op_sel_hi:[0,1,0]
	v_fma_mix_f32 v53, v87, v47, v53 op_sel:[0,1,0] op_sel_hi:[0,1,0]
	v_fma_mix_f32 v40, v87, v41, v40 op_sel:[0,1,0] op_sel_hi:[0,1,0]
	v_fma_mix_f32 v55, v93, v50, 0 op_sel:[1,0,0] op_sel_hi:[1,1,0]
	v_fma_mix_f32 v58, v93, v50, 0 op_sel:[1,1,0] op_sel_hi:[1,1,0]
	v_add_f32_dpp v53, v53, v53 quad_perm:[1,0,3,2] row_mask:0xf bank_mask:0xf bound_ctrl:1
	v_fma_mix_f32 v59, v93, v51, 0 op_sel:[1,0,0] op_sel_hi:[1,1,0]
	v_fma_mix_f32 v60, v93, v51, 0 op_sel:[1,1,0] op_sel_hi:[1,1,0]
	v_add_f32_dpp v53, v53, v53 quad_perm:[2,3,0,1] row_mask:0xf bank_mask:0xf bound_ctrl:1
	v_fma_mix_f32 v84, v84, v44, v55 op_sel:[0,0,0] op_sel_hi:[0,1,0]
	v_fma_mix_f32 v85, v85, v44, v58 op_sel:[0,1,0] op_sel_hi:[0,1,0]
	v_add_f32_dpp v53, v53, v53 row_half_mirror row_mask:0xf bank_mask:0xf bound_ctrl:1
	v_fma_mix_f32 v86, v86, v45, v59 op_sel:[0,0,0] op_sel_hi:[0,1,0]
	v_fma_mix_f32 v87, v87, v45, v60 op_sel:[0,1,0] op_sel_hi:[0,1,0]
	v_add_f32_dpp v53, v53, v53 row_mirror row_mask:0xf bank_mask:0xf bound_ctrl:1
	v_fma_mix_f32 v84, -v53, v48, v84 op_sel:[0,0,0] op_sel_hi:[0,1,0]
	v_fma_mix_f32 v85, -v53, v48, v85 op_sel:[0,1,0] op_sel_hi:[0,1,0]
	v_fma_mix_f32 v86, -v53, v49, v86 op_sel:[0,0,0] op_sel_hi:[0,1,0]
	v_fma_mix_f32 v87, -v53, v49, v87 op_sel:[0,1,0] op_sel_hi:[0,1,0]
	v_fma_mix_f32 v41, v84, v42, 0 op_sel:[0,0,0] op_sel_hi:[0,1,0]
	v_fma_mix_f32 v41, v85, v42, v41 op_sel:[0,1,0] op_sel_hi:[0,1,0]
	v_fma_mix_f32 v41, v86, v43, v41 op_sel:[0,0,0] op_sel_hi:[0,1,0]
	v_fma_mix_f32 v41, v87, v43, v41 op_sel:[0,1,0] op_sel_hi:[0,1,0]
	v_cndmask_b32_e64 v43, v57, v56, s[38:39]
	v_cndmask_b32_e64 v44, v56, v57, s[38:39]
	s_add_i32 s4, s33, 3
	s_mov_b32 s33, s34
	v_add_f32_dpp v43, v44, v43 quad_perm:[1,0,3,2] row_mask:0xf bank_mask:0xf bound_ctrl:1
	v_cndmask_b32_e64 v44, v41, v40, s[38:39]
	v_cndmask_b32_e64 v40, v40, v41, s[38:39]
	s_and_b32 s4, s4, 15
	s_mulk_i32 s4, 0xc00
	v_add_f32_dpp v40, v40, v44 quad_perm:[1,0,3,2] row_mask:0xf bank_mask:0xf bound_ctrl:1
	v_cndmask_b32_e64 v41, v40, v43, s[40:41]
	v_cndmask_b32_e64 v40, v43, v40, s[40:41]
	s_add_i32 s4, s4, 16
	v_add_u32_e32 v178, s4, v177
	v_add_f32_dpp v40, v40, v41 quad_perm:[2,3,0,1] row_mask:0xf bank_mask:0xf bound_ctrl:1
	v_add_u32_e32 v179, s4, v117
	v_add_u32_e32 v180, s4, v184
	v_add_f32_dpp v40, v40, v40 row_ror:4 row_mask:0xf bank_mask:0xf bound_ctrl:1
	v_mov_b32_e32 v173, s34
	ds_write_b32 v172, v173 offset:49216
	v_add_f32_dpp v40, v40, v40 row_ror:8 row_mask:0xf bank_mask:0xf bound_ctrl:1
	v_cvt_f16_f32_e32 v40, v40
	global_store_short v83, v40, s[36:37]
	s_add_u32 s36, s36, s44
	s_addc_u32 s37, s37, s45
	s_cmp_eq_u32 s34, 64
	s_cbranch_scc1 .Lc_fix
